# nt (streaming) hints also on the final-norm loads/stores and on attn0's read-once K/V LDS-DMA, Q and previous-O loads
# baseline (speedup 1.0000x reference)
.LBB0_155:
	v_lshl_add_u64 v[26:27], s[0:1], 0, v[24:25]
	v_add_co_u32_e32 v28, vcc, 0x5000000, v26
	s_add_u32 s12, s0, s10
	s_nop 0
	v_addc_co_u32_e32 v29, vcc, 0, v27, vcc
	s_mov_b32 s2, 0x5001000
	s_addc_u32 s13, s1, s11
	v_add_co_u32_e32 v26, vcc, s2, v26
	s_add_u32 s2, s12, 0x700000
	s_nop 0
	v_addc_co_u32_e32 v27, vcc, 0, v27, vcc
	s_addc_u32 s3, s13, 0
	global_load_dwordx2 v[60:61], v[28:29], off nt
	global_load_dwordx2 v[56:57], v[28:29], off offset:512 nt
	global_load_dwordx2 v[20:21], v[28:29], off offset:1024 nt
	global_load_dwordx2 v[18:19], v[28:29], off offset:1536 nt
	global_load_dwordx2 v[48:49], v[28:29], off offset:2048 nt
	global_load_dwordx2 v[46:47], v[28:29], off offset:2560 nt
	global_load_dwordx2 v[44:45], v[28:29], off offset:3072 nt
	global_load_dwordx2 v[40:41], v[28:29], off offset:3584 nt
	global_load_dwordx2 v[42:43], v[26:27], off nt
	global_load_dwordx2 v[38:39], v[26:27], off offset:512 nt
	global_load_dwordx2 v[36:37], v[26:27], off offset:1024 nt
	global_load_dwordx2 v[34:35], v[26:27], off offset:1536 nt
	global_load_dwordx2 v[32:33], v[26:27], off offset:2048 nt
	global_load_dwordx2 v[30:31], v[26:27], off offset:2560 nt
	global_load_dwordx2 v[28:29], v[26:27], off offset:3072 nt
	s_nop 0
	global_load_dwordx2 v[26:27], v[26:27], off offset:3584 nt
	s_nop 0
	global_load_dwordx4 v[50:53], v0, s[2:3] offset:48 nt
	global_load_dwordx4 v[62:65], v0, s[2:3] offset:32 nt
	global_load_dwordx4 v[66:69], v0, s[2:3] offset:16 nt
	global_load_dwordx4 v[70:73], v78, s[12:13] nt
	v_lshl_add_u64 v[24:25], v[24:25], 0, s[26:27]
	s_waitcnt vmcnt(2)
	v_add_f32_e32 v62, v62, v63
	s_waitcnt vmcnt(1)
	v_mov_b32_e32 v58, v67
	s_waitcnt vmcnt(0)
	v_mov_b32_e32 v54, v71
	v_mov_b32_e32 v55, v72
	v_mov_b32_e32 v71, v73
	v_mov_b32_e32 v59, v68
	v_mov_b32_e32 v67, v69
	v_pk_add_f32 v[54:55], v[54:55], v[70:71]
	v_pk_add_f32 v[58:59], v[58:59], v[66:67]
	v_pk_add_f32 v[54:55], v[54:55], v[54:55] op_sel:[0,1] op_sel_hi:[1,0]
	v_pk_add_f32 v[58:59], v[58:59], v[58:59] op_sel:[0,1] op_sel_hi:[1,0]
	v_add_f32_e32 v64, v64, v65
	v_mov_b32_e32 v55, v50
	v_mov_b32_e32 v59, v51
	v_mov_b32_e32 v63, v52
	v_mov_b32_e32 v65, v53
	v_pk_add_f32 v[50:51], v[54:55], v[58:59]
	v_pk_add_f32 v[52:53], v[62:63], v[64:65]
	s_nop 0
	v_pk_add_f32 v[50:51], v[50:51], v[52:53]
	s_nop 0
	v_add_f32_e32 v1, v50, v51
	v_fmamk_f32 v1, v1, 0x3a800000, v235
	v_cmp_gt_f32_e32 vcc, s64, v1
	v_mul_f32_e32 v50, 0x4f800000, v1
	s_nop 0
	v_cndmask_b32_e32 v1, v1, v50, vcc
	v_sqrt_f32_e32 v50, v1
	s_nop 0
	v_add_u32_e32 v51, -1, v50
	v_fma_f32 v52, -v51, v50, v1
	v_cmp_ge_f32_e64 s[2:3], 0, v52
	v_add_u32_e32 v52, 1, v50
	s_nop 0
	v_cndmask_b32_e64 v51, v50, v51, s[2:3]
	v_fma_f32 v50, -v52, v50, v1
	v_cmp_lt_f32_e64 s[2:3], 0, v50
	s_nop 1
	v_cndmask_b32_e64 v50, v51, v52, s[2:3]
	v_mul_f32_e32 v51, 0x37800000, v50
	v_cndmask_b32_e32 v50, v50, v51, vcc
	v_cmp_class_f32_e32 vcc, v1, v79
	s_nop 1
	v_cndmask_b32_e32 v1, v50, v1, vcc
	v_div_scale_f32 v50, s[2:3], v1, v1, 1.0
	v_rcp_f32_e32 v51, v50
	s_add_u32 s2, s12, 0x700040
	s_addc_u32 s3, s13, 0
	v_fma_f32 v52, -v50, v51, 1.0
	v_fmac_f32_e32 v51, v52, v51
	v_div_scale_f32 v52, vcc, 1.0, v1, 1.0
	v_mul_f32_e32 v53, v52, v51
	v_fma_f32 v54, -v50, v53, v52
	v_fmac_f32_e32 v53, v54, v51
	v_fma_f32 v50, -v50, v53, v52
	v_div_fmas_f32 v50, v50, v51, v53
	v_div_fixup_f32 v58, v50, v1, 1.0
	global_load_dwordx4 v[50:53], v0, s[2:3] offset:48 nt
	global_load_dwordx4 v[62:65], v0, s[2:3] offset:32 nt
	global_load_dwordx4 v[66:69], v0, s[2:3] offset:16 nt
	global_load_dwordx4 v[70:73], v78, s[12:13] offset:64 nt
	s_waitcnt vmcnt(2)
	v_add_f32_e32 v62, v62, v63
	v_add_f32_e32 v64, v64, v65
	s_waitcnt vmcnt(0)
	v_mov_b32_e32 v54, v71
	v_mov_b32_e32 v55, v72
	v_mov_b32_e32 v71, v73
	v_pk_add_f32 v[54:55], v[54:55], v[70:71]
	v_mov_b32_e32 v70, v67
	v_mov_b32_e32 v71, v68
	v_mov_b32_e32 v67, v69
	v_pk_add_f32 v[66:67], v[70:71], v[66:67]
	v_pk_add_f32 v[54:55], v[54:55], v[54:55] op_sel:[0,1] op_sel_hi:[1,0]
	v_pk_add_f32 v[66:67], v[66:67], v[66:67] op_sel:[0,1] op_sel_hi:[1,0]
	v_mov_b32_e32 v55, v50
	v_mov_b32_e32 v67, v51
	v_mov_b32_e32 v63, v52
	v_mov_b32_e32 v65, v53
	v_pk_add_f32 v[50:51], v[54:55], v[66:67]
	v_pk_add_f32 v[52:53], v[62:63], v[64:65]
	s_nop 0
	v_pk_add_f32 v[50:51], v[50:51], v[52:53]
	s_nop 0
	v_add_f32_e32 v1, v50, v51
	v_fmamk_f32 v1, v1, 0x3a800000, v235
	v_cmp_gt_f32_e32 vcc, s64, v1
	v_mul_f32_e32 v50, 0x4f800000, v1
	s_nop 0
	v_cndmask_b32_e32 v1, v1, v50, vcc
	v_sqrt_f32_e32 v50, v1
	s_nop 0
	v_add_u32_e32 v51, -1, v50
	v_fma_f32 v52, -v51, v50, v1
	v_cmp_ge_f32_e64 s[2:3], 0, v52
	v_add_u32_e32 v52, 1, v50
	s_nop 0
	v_cndmask_b32_e64 v51, v50, v51, s[2:3]
	v_fma_f32 v50, -v52, v50, v1
	v_cmp_lt_f32_e64 s[2:3], 0, v50
	s_nop 1
	v_cndmask_b32_e64 v50, v51, v52, s[2:3]
	v_mul_f32_e32 v51, 0x37800000, v50
	v_cndmask_b32_e32 v50, v50, v51, vcc
	v_cmp_class_f32_e32 vcc, v1, v79
	s_nop 1
	v_cndmask_b32_e32 v1, v50, v1, vcc
	v_div_scale_f32 v50, s[2:3], v1, v1, 1.0
	v_rcp_f32_e32 v51, v50
	s_add_u32 s2, s12, 0x700080
	s_addc_u32 s3, s13, 0
	v_fma_f32 v52, -v50, v51, 1.0
	v_fmac_f32_e32 v51, v52, v51
	v_div_scale_f32 v52, vcc, 1.0, v1, 1.0
	v_mul_f32_e32 v53, v52, v51
	v_fma_f32 v54, -v50, v53, v52
	v_fmac_f32_e32 v53, v54, v51
	v_fma_f32 v50, -v50, v53, v52
	v_div_fmas_f32 v50, v50, v51, v53
	v_div_fixup_f32 v54, v50, v1, 1.0
	global_load_dwordx4 v[50:53], v0, s[2:3] offset:48 nt
	global_load_dwordx4 v[62:65], v0, s[2:3] offset:32 nt
	global_load_dwordx4 v[66:69], v0, s[2:3] offset:16 nt
	global_load_dwordx4 v[70:73], v78, s[12:13] offset:128 nt
	s_waitcnt vmcnt(2)
	v_add_f32_e32 v62, v62, v63
	v_add_f32_e32 v64, v64, v65
	s_waitcnt vmcnt(0)
	v_mov_b32_e32 v74, v71
	v_mov_b32_e32 v75, v72
	v_mov_b32_e32 v71, v73
	v_mov_b32_e32 v72, v67
	v_mov_b32_e32 v73, v68
	v_mov_b32_e32 v67, v69
	v_pk_add_f32 v[70:71], v[74:75], v[70:71]
	v_pk_add_f32 v[66:67], v[72:73], v[66:67]
	v_pk_add_f32 v[70:71], v[70:71], v[70:71] op_sel:[0,1] op_sel_hi:[1,0]
	v_pk_add_f32 v[66:67], v[66:67], v[66:67] op_sel:[0,1] op_sel_hi:[1,0]
	v_mov_b32_e32 v71, v50
	v_mov_b32_e32 v67, v51
	v_mov_b32_e32 v63, v52
	v_mov_b32_e32 v65, v53
	v_pk_add_f32 v[50:51], v[70:71], v[66:67]
	v_pk_add_f32 v[52:53], v[62:63], v[64:65]
	s_nop 0
	v_pk_add_f32 v[50:51], v[50:51], v[52:53]
	s_nop 0
	v_add_f32_e32 v1, v50, v51
	v_fmamk_f32 v1, v1, 0x3a800000, v235
	v_cmp_gt_f32_e32 vcc, s64, v1
	v_mul_f32_e32 v50, 0x4f800000, v1
	s_nop 0
	v_cndmask_b32_e32 v1, v1, v50, vcc
	v_sqrt_f32_e32 v50, v1
	s_nop 0
	v_add_u32_e32 v51, -1, v50
	v_fma_f32 v52, -v51, v50, v1
	v_cmp_ge_f32_e64 s[2:3], 0, v52
	v_add_u32_e32 v52, 1, v50
	s_nop 0
	v_cndmask_b32_e64 v51, v50, v51, s[2:3]
	v_fma_f32 v50, -v52, v50, v1
	v_cmp_lt_f32_e64 s[2:3], 0, v50
	s_nop 1
	v_cndmask_b32_e64 v50, v51, v52, s[2:3]
	v_mul_f32_e32 v51, 0x37800000, v50
	v_cndmask_b32_e32 v50, v50, v51, vcc
	v_cmp_class_f32_e32 vcc, v1, v79
	s_nop 1
	v_cndmask_b32_e32 v1, v50, v1, vcc
	v_div_scale_f32 v50, s[2:3], v1, v1, 1.0
	s_add_u32 s2, s12, 0x7000c0
	s_addc_u32 s3, s13, 0
	s_nop 2
	global_load_dwordx4 v[62:65], v0, s[2:3] offset:48 nt
	global_load_dwordx4 v[66:69], v0, s[2:3] offset:32 nt
	global_load_dwordx4 v[70:73], v0, s[2:3] offset:16 nt
	global_load_dwordx4 v[74:77], v78, s[12:13] offset:192 nt
	v_rcp_f32_e32 v51, v50
	s_add_i32 s6, s6, s14
	s_add_u32 s10, s10, s20
	s_addc_u32 s11, s11, s21
	v_fma_f32 v52, -v50, v51, 1.0
	v_fmac_f32_e32 v51, v52, v51
	v_div_scale_f32 v52, vcc, 1.0, v1, 1.0
	v_mul_f32_e32 v53, v52, v51
	v_fma_f32 v55, -v50, v53, v52
	v_fmac_f32_e32 v53, v55, v51
	v_fma_f32 v50, -v50, v53, v52
	v_div_fmas_f32 v50, v50, v51, v53
	v_div_fixup_f32 v50, v50, v1, 1.0
	s_cmp_lt_i32 s6, 0x8000
	s_waitcnt vmcnt(2)
	v_add_f32_e32 v66, v66, v67
	v_add_f32_e32 v68, v68, v69
	s_waitcnt vmcnt(0)
	v_mov_b32_e32 v52, v75
	v_mov_b32_e32 v53, v76
	v_mov_b32_e32 v75, v77
	v_pk_add_f32 v[52:53], v[52:53], v[74:75]
	v_mov_b32_e32 v74, v71
	v_mov_b32_e32 v75, v72
	v_mov_b32_e32 v71, v73
	v_pk_add_f32 v[70:71], v[74:75], v[70:71]
	v_pk_add_f32 v[52:53], v[52:53], v[52:53] op_sel:[0,1] op_sel_hi:[1,0]
	v_pk_add_f32 v[70:71], v[70:71], v[70:71] op_sel:[0,1] op_sel_hi:[1,0]
	v_mov_b32_e32 v53, v62
	v_mov_b32_e32 v71, v63
	v_mov_b32_e32 v67, v64
	v_mov_b32_e32 v69, v65
	v_pk_add_f32 v[52:53], v[52:53], v[70:71]
	v_pk_add_f32 v[62:63], v[66:67], v[68:69]
	s_nop 0
	v_pk_add_f32 v[52:53], v[52:53], v[62:63]
	v_lshlrev_b32_e32 v62, 16, v60
	v_add_f32_e32 v1, v52, v53
	v_fmamk_f32 v1, v1, 0x3a800000, v235
	v_cmp_gt_f32_e32 vcc, s64, v1
	v_mul_f32_e32 v51, 0x4f800000, v1
	v_and_b32_e32 v63, 0xffff0000, v60
	v_cndmask_b32_e32 v1, v1, v51, vcc
	v_sqrt_f32_e32 v51, v1
	v_lshlrev_b32_e32 v60, 16, v61
	v_and_b32_e32 v61, 0xffff0000, v61
	v_add_u32_e32 v52, -1, v51
	v_fma_f32 v53, -v52, v51, v1
	v_cmp_ge_f32_e64 s[2:3], 0, v53
	v_add_u32_e32 v53, 1, v51
	s_nop 0
	v_cndmask_b32_e64 v52, v51, v52, s[2:3]
	v_fma_f32 v51, -v53, v51, v1
	v_cmp_lt_f32_e64 s[2:3], 0, v51
	s_nop 1
	v_cndmask_b32_e64 v51, v52, v53, s[2:3]
	v_mul_f32_e32 v52, 0x37800000, v51
	v_cndmask_b32_e32 v51, v51, v52, vcc
	v_cmp_class_f32_e32 vcc, v1, v79
	s_nop 1
	v_cndmask_b32_e32 v1, v51, v1, vcc
	v_div_scale_f32 v51, s[2:3], v1, v1, 1.0
	v_rcp_f32_e32 v52, v51
	s_movk_i32 s2, 0xd000
	v_fma_f32 v53, -v51, v52, 1.0
	v_fmac_f32_e32 v52, v53, v52
	v_div_scale_f32 v53, vcc, 1.0, v1, 1.0
	v_mul_f32_e32 v55, v53, v52
	v_fma_f32 v59, -v51, v55, v53
	v_fmac_f32_e32 v55, v59, v52
	v_fma_f32 v51, -v51, v55, v53
	v_pk_mul_f32 v[64:65], v[58:59], v[62:63] op_sel_hi:[0,1]
	v_pk_mul_f32 v[60:61], v[58:59], v[60:61] op_sel_hi:[0,1]
	v_div_fmas_f32 v51, v51, v52, v55
	v_pk_mul_f32 v[62:63], v[4:5], v[60:61]
	v_pk_mul_f32 v[60:61], v[2:3], v[64:65]
	v_add_co_u32_e32 v64, vcc, s2, v22
	s_movk_i32 s2, 0xe000
	s_nop 0
	v_addc_co_u32_e32 v65, vcc, -1, v23, vcc
	global_store_dwordx4 v[64:65], v[60:63], off offset:-3072 nt
	v_div_fixup_f32 v52, v51, v1, 1.0
	s_nop 0
	v_lshlrev_b32_e32 v60, 16, v56
	v_and_b32_e32 v61, 0xffff0000, v56
	v_lshlrev_b32_e32 v56, 16, v57
	v_and_b32_e32 v57, 0xffff0000, v57
	v_pk_mul_f32 v[56:57], v[58:59], v[56:57] op_sel_hi:[0,1]
	v_pk_mul_f32 v[60:61], v[58:59], v[60:61] op_sel_hi:[0,1]
	v_pk_mul_f32 v[62:63], v[8:9], v[56:57]
	v_lshlrev_b32_e32 v56, 16, v20
	v_and_b32_e32 v57, 0xffff0000, v20
	v_lshlrev_b32_e32 v20, 16, v21
	v_and_b32_e32 v21, 0xffff0000, v21
	v_pk_mul_f32 v[60:61], v[6:7], v[60:61]
	v_pk_mul_f32 v[20:21], v[58:59], v[20:21] op_sel_hi:[0,1]
	global_store_dwordx4 v[64:65], v[60:63], off offset:-2048 nt
	v_pk_mul_f32 v[56:57], v[58:59], v[56:57] op_sel_hi:[0,1]
	s_nop 0
	v_pk_mul_f32 v[62:63], v[12:13], v[20:21]
	v_lshlrev_b32_e32 v20, 16, v18
	v_and_b32_e32 v21, 0xffff0000, v18
	v_lshlrev_b32_e32 v18, 16, v19
	v_and_b32_e32 v19, 0xffff0000, v19
	v_pk_mul_f32 v[60:61], v[10:11], v[56:57]
	v_pk_mul_f32 v[56:57], v[58:59], v[20:21] op_sel_hi:[0,1]
	v_pk_mul_f32 v[18:19], v[58:59], v[18:19] op_sel_hi:[0,1]
	v_pk_mul_f32 v[20:21], v[16:17], v[18:19]
	v_pk_mul_f32 v[18:19], v[14:15], v[56:57]
	v_add_co_u32_e32 v56, vcc, s2, v22
	s_movk_i32 s2, 0xf000
	s_nop 0
	v_addc_co_u32_e32 v57, vcc, -1, v23, vcc
	global_store_dwordx4 v[56:57], v[18:21], off offset:-4096 nt
	global_store_dwordx4 v[64:65], v[60:63], off offset:-1024 nt
	s_nop 0
	v_lshlrev_b32_e32 v18, 16, v48
	v_and_b32_e32 v19, 0xffff0000, v48
	v_lshlrev_b32_e32 v20, 16, v49
	v_and_b32_e32 v21, 0xffff0000, v49
	v_pk_mul_f32 v[18:19], v[54:55], v[18:19] op_sel_hi:[0,1]
	v_pk_mul_f32 v[20:21], v[54:55], v[20:21] op_sel_hi:[0,1]
	v_pk_mul_f32 v[20:21], v[4:5], v[20:21]
	v_pk_mul_f32 v[18:19], v[2:3], v[18:19]
	global_store_dwordx4 v[56:57], v[18:21], off offset:-3072 nt
	s_nop 1
	v_lshlrev_b32_e32 v18, 16, v46
	v_and_b32_e32 v19, 0xffff0000, v46
	v_lshlrev_b32_e32 v20, 16, v47
	v_and_b32_e32 v21, 0xffff0000, v47
	v_pk_mul_f32 v[18:19], v[54:55], v[18:19] op_sel_hi:[0,1]
	v_pk_mul_f32 v[20:21], v[54:55], v[20:21] op_sel_hi:[0,1]
	v_pk_mul_f32 v[20:21], v[8:9], v[20:21]
	v_pk_mul_f32 v[18:19], v[6:7], v[18:19]
	global_store_dwordx4 v[56:57], v[18:21], off offset:-2048 nt
	s_nop 1
	v_lshlrev_b32_e32 v18, 16, v44
	v_and_b32_e32 v19, 0xffff0000, v44
	v_lshlrev_b32_e32 v20, 16, v45
	v_and_b32_e32 v21, 0xffff0000, v45
	v_pk_mul_f32 v[18:19], v[54:55], v[18:19] op_sel_hi:[0,1]
	v_pk_mul_f32 v[20:21], v[54:55], v[20:21] op_sel_hi:[0,1]
	v_pk_mul_f32 v[20:21], v[12:13], v[20:21]
	v_pk_mul_f32 v[18:19], v[10:11], v[18:19]
	global_store_dwordx4 v[56:57], v[18:21], off offset:-1024 nt
	s_nop 1
	v_lshlrev_b32_e32 v18, 16, v40
	v_and_b32_e32 v19, 0xffff0000, v40
	v_lshlrev_b32_e32 v20, 16, v41
	v_and_b32_e32 v21, 0xffff0000, v41
	v_pk_mul_f32 v[18:19], v[54:55], v[18:19] op_sel_hi:[0,1]
	v_pk_mul_f32 v[20:21], v[54:55], v[20:21] op_sel_hi:[0,1]
	v_pk_mul_f32 v[20:21], v[16:17], v[20:21]
	v_pk_mul_f32 v[18:19], v[14:15], v[18:19]
	global_store_dwordx4 v[56:57], v[18:21], off nt
	v_add_co_u32_e32 v40, vcc, s2, v22
	s_nop 0
	v_lshlrev_b32_e32 v18, 16, v42
	v_and_b32_e32 v19, 0xffff0000, v42
	v_lshlrev_b32_e32 v20, 16, v43
	v_and_b32_e32 v21, 0xffff0000, v43
	v_pk_mul_f32 v[18:19], v[50:51], v[18:19] op_sel_hi:[0,1]
	v_pk_mul_f32 v[20:21], v[50:51], v[20:21] op_sel_hi:[0,1]
	v_pk_mul_f32 v[20:21], v[4:5], v[20:21]
	v_pk_mul_f32 v[18:19], v[2:3], v[18:19]
	v_addc_co_u32_e32 v41, vcc, -1, v23, vcc
	global_store_dwordx4 v[40:41], v[18:21], off offset:-3072 nt
	s_nop 1
	v_lshlrev_b32_e32 v18, 16, v38
	v_and_b32_e32 v19, 0xffff0000, v38
	v_lshlrev_b32_e32 v20, 16, v39
	v_and_b32_e32 v21, 0xffff0000, v39
	v_pk_mul_f32 v[18:19], v[50:51], v[18:19] op_sel_hi:[0,1]
	v_pk_mul_f32 v[20:21], v[50:51], v[20:21] op_sel_hi:[0,1]
	v_pk_mul_f32 v[20:21], v[8:9], v[20:21]
	v_pk_mul_f32 v[18:19], v[6:7], v[18:19]
	global_store_dwordx4 v[40:41], v[18:21], off offset:-2048 nt
	s_nop 1
	v_lshlrev_b32_e32 v18, 16, v36
	v_and_b32_e32 v19, 0xffff0000, v36
	v_lshlrev_b32_e32 v20, 16, v37
	v_and_b32_e32 v21, 0xffff0000, v37
	v_pk_mul_f32 v[18:19], v[50:51], v[18:19] op_sel_hi:[0,1]
	v_pk_mul_f32 v[20:21], v[50:51], v[20:21] op_sel_hi:[0,1]
	v_pk_mul_f32 v[20:21], v[12:13], v[20:21]
	v_pk_mul_f32 v[18:19], v[10:11], v[18:19]
	global_store_dwordx4 v[40:41], v[18:21], off offset:-1024 nt
	s_nop 1
	v_lshlrev_b32_e32 v18, 16, v34
	v_and_b32_e32 v19, 0xffff0000, v34
	v_lshlrev_b32_e32 v20, 16, v35
	v_and_b32_e32 v21, 0xffff0000, v35
	v_pk_mul_f32 v[18:19], v[50:51], v[18:19] op_sel_hi:[0,1]
	v_pk_mul_f32 v[20:21], v[50:51], v[20:21] op_sel_hi:[0,1]
	v_pk_mul_f32 v[20:21], v[16:17], v[20:21]
	v_pk_mul_f32 v[18:19], v[14:15], v[18:19]
	global_store_dwordx4 v[22:23], v[18:21], off offset:-4096 nt
	s_nop 1
	v_lshlrev_b32_e32 v18, 16, v32
	v_and_b32_e32 v19, 0xffff0000, v32
	v_lshlrev_b32_e32 v20, 16, v33
	v_and_b32_e32 v21, 0xffff0000, v33
	v_pk_mul_f32 v[18:19], v[52:53], v[18:19] op_sel_hi:[0,1]
	v_pk_mul_f32 v[20:21], v[52:53], v[20:21] op_sel_hi:[0,1]
	v_pk_mul_f32 v[20:21], v[4:5], v[20:21]
	v_pk_mul_f32 v[18:19], v[2:3], v[18:19]
	global_store_dwordx4 v[22:23], v[18:21], off offset:-3072 nt
	s_nop 1
	v_lshlrev_b32_e32 v18, 16, v30
	v_and_b32_e32 v19, 0xffff0000, v30
	v_lshlrev_b32_e32 v20, 16, v31
	v_and_b32_e32 v21, 0xffff0000, v31
	v_pk_mul_f32 v[18:19], v[52:53], v[18:19] op_sel_hi:[0,1]
	v_pk_mul_f32 v[20:21], v[52:53], v[20:21] op_sel_hi:[0,1]
	v_pk_mul_f32 v[20:21], v[8:9], v[20:21]
	v_pk_mul_f32 v[18:19], v[6:7], v[18:19]
	global_store_dwordx4 v[22:23], v[18:21], off offset:-2048 nt
	s_nop 1
	v_lshlrev_b32_e32 v18, 16, v28
	v_and_b32_e32 v19, 0xffff0000, v28
	v_lshlrev_b32_e32 v20, 16, v29
	v_and_b32_e32 v21, 0xffff0000, v29
	v_pk_mul_f32 v[18:19], v[52:53], v[18:19] op_sel_hi:[0,1]
	v_pk_mul_f32 v[20:21], v[52:53], v[20:21] op_sel_hi:[0,1]
	v_pk_mul_f32 v[20:21], v[12:13], v[20:21]
	v_pk_mul_f32 v[18:19], v[10:11], v[18:19]
	global_store_dwordx4 v[22:23], v[18:21], off offset:-1024 nt
	s_nop 1
	v_lshlrev_b32_e32 v18, 16, v26
	v_and_b32_e32 v19, 0xffff0000, v26
	v_lshlrev_b32_e32 v20, 16, v27
	v_and_b32_e32 v21, 0xffff0000, v27
	v_pk_mul_f32 v[18:19], v[52:53], v[18:19] op_sel_hi:[0,1]
	v_pk_mul_f32 v[20:21], v[52:53], v[20:21] op_sel_hi:[0,1]
	v_pk_mul_f32 v[20:21], v[16:17], v[20:21]
	v_pk_mul_f32 v[18:19], v[14:15], v[18:19]
	global_store_dwordx4 v[22:23], v[18:21], off nt
	v_lshl_add_u64 v[22:23], v[22:23], 0, s[16:17]
	s_cbranch_scc1 .LBB0_155

.LBB0_440:
	s_and_b32 vcc_lo, s85, 0x1e000
	s_add_i32 vcc_lo, s75, vcc_lo
	s_mov_b32 vcc_hi, m0
	s_mov_b32 m0, vcc_lo
	s_nop 0
	global_load_lds_dwordx4 v[2:3], off nt
	s_mov_b32 m0, vcc_hi
	s_add_i32 s69, s69, 1
	s_addk_i32 s85, 0x2000
	s_cmp_ge_i32 s69, s68
	v_lshl_add_u64 v[2:3], v[2:3], 0, s[78:79]
	s_cbranch_scc0 .LBB0_440
	s_add_i32 s72, s72, s71
	s_lshl_b32 s68, s72, 5
	s_lshl_b32 s98, s72, 12
	s_mov_b32 s99, 0
	v_lshl_add_u64 v[2:3], v[142:143], 0, s[98:99]
	global_load_dwordx4 v[92:95], v[2:3], off nt
	global_load_dwordx4 v[88:91], v[2:3], off offset:1024 nt
	global_load_dwordx4 v[84:87], v[2:3], off offset:2048 nt
	global_load_dwordx4 v[80:83], v[2:3], off offset:3072 nt
	s_ashr_i32 s69, s68, s76
	s_and_b32 s68, s68, s73
	v_or_b32_e32 v1, s68, v150
	v_lshlrev_b32_e32 v1, s33, v1
	s_add_i32 s69, s69, s87
	v_add_u32_e32 v2, s69, v1
	v_ashrrev_i32_e32 v3, 31, v2
	v_lshlrev_b64 v[4:5], 11, v[2:3]
	v_lshlrev_b64 v[2:3], 6, v[2:3]
	v_lshl_add_u64 v[148:149], v[144:145], 0, v[4:5]
	s_and_b64 vcc, exec, s[88:89]
	v_lshl_add_u64 v[146:147], s[82:83], 0, v[2:3]
	s_cbranch_vccz .LBB0_443
	global_load_dword v154, v[146:147], off
	global_load_dwordx2 v[138:139], v[148:149], off nt
	global_load_dwordx2 v[136:137], v[148:149], off offset:16 nt
	global_load_dwordx2 v[134:135], v[148:149], off offset:32 nt
	global_load_dwordx2 v[132:133], v[148:149], off offset:48 nt
	global_load_dwordx2 v[130:131], v[148:149], off offset:64 nt
	global_load_dwordx2 v[128:129], v[148:149], off offset:80 nt
	global_load_dwordx2 v[126:127], v[148:149], off offset:96 nt
	global_load_dwordx2 v[124:125], v[148:149], off offset:112 nt
	s_branch .LBB0_444
